# P2 epilogue: the 8 row-block store addresses are SGPR base + 32-bit VGPR offset (one v_mad_u32_u24 each) instead of v_mov_b64 + v_mad_i64_i32 + v_lshl_add_u64
# speedup vs baseline: 1.0046x; 1.0014x over previous
.LBB0_205:
	s_add_i32 s5, s4, -8
	s_cmp_gt_i32 s4, 15
	s_cselect_b64 s[30:31], -1, 0
	s_lshl_b32 s19, s4, 8
	v_mov_b32_e32 v175, v145
	v_mov_b32_e32 v52, v147
	s_or_b32 s19, s19, s56
	s_cmp_gt_i32 s4, 5
	v_lshl_add_u32 v164, v52, 3, s19
	v_ashrrev_i32_e32 v165, 31, v164
	v_lshlrev_b32_e32 v248, 1, v164
	v_lshl_add_u64 v[60:61], v[164:165], 2, s[10:11]
	v_mov_b32_e32 v72, v232
	v_mov_b32_e32 v73, v233
	v_mov_b32_e32 v74, v234
	v_mov_b32_e32 v75, v235
	v_mov_b32_e32 v64, v236
	v_mov_b32_e32 v65, v237
	v_mov_b32_e32 v66, v238
	v_mov_b32_e32 v67, v239
	v_mov_b32_e32 v52, v240
	v_mov_b32_e32 v53, v241
	v_mov_b32_e32 v54, v242
	v_mov_b32_e32 v55, v243
	s_nop 0
	v_mov_b32_e32 v60, v244
	v_mov_b32_e32 v61, v245
	v_mov_b32_e32 v62, v246
	v_mov_b32_e32 v63, v247
	s_cselect_b64 s[28:29], -1, 0
	s_cmp_lt_u32 s5, 6
	s_cselect_b64 s[4:5], -1, 0
	s_or_b64 s[4:5], s[30:31], s[4:5]
	s_and_b64 s[30:31], s[28:29], s[4:5]
	v_cndmask_b32_e64 v166, 0, 1, s[30:31]
	v_cmp_ne_u32_e64 s[4:5], 1, v166
	s_andn2_b64 vcc, exec, s[30:31]
	s_waitcnt vmcnt(0)
	v_pk_add_f32 v[166:167], v[142:143], v[74:75]
	v_pk_add_f32 v[168:169], v[140:141], v[72:73]
	v_pk_add_f32 v[140:141], v[138:139], v[66:67]
	v_pk_add_f32 v[142:143], v[136:137], v[64:65]
	s_cbranch_vccnz .LBB0_207
	v_mul_f32_e32 v137, 0xbfb8aa3b, v142
	v_mul_f32_e32 v138, 0xbfb8aa3b, v169
	v_exp_f32_e32 v137, v137
	v_exp_f32_e32 v139, v138
	v_mul_f32_e32 v177, 0xbfb8aa3b, v140
	v_mul_f32_e32 v178, 0xbfb8aa3b, v167
	v_add_f32_e32 v137, 1.0, v137
	v_mul_f32_e32 v136, 0xbfb8aa3b, v168
	v_rcp_f32_e32 v138, v137
	v_add_f32_e32 v137, 1.0, v139
	v_mul_f32_e32 v139, 0xbfb8aa3b, v143
	v_mul_f32_e32 v176, 0xbfb8aa3b, v166
	v_exp_f32_e32 v177, v177
	v_exp_f32_e32 v179, v178
	v_mul_f32_e32 v178, 0xbfb8aa3b, v141
	v_exp_f32_e32 v136, v136
	v_exp_f32_e32 v139, v139
	v_exp_f32_e32 v176, v176
	v_exp_f32_e32 v180, v178
	v_add_f32_e32 v177, 1.0, v177
	v_add_f32_e32 v136, 1.0, v136
	v_add_f32_e32 v139, 1.0, v139
	v_add_f32_e32 v176, 1.0, v176
	v_rcp_f32_e32 v178, v177
	v_add_f32_e32 v177, 1.0, v179
	v_add_f32_e32 v179, 1.0, v180
	v_rcp_f32_e32 v136, v136
	v_rcp_f32_e32 v137, v137
	v_rcp_f32_e32 v176, v176
	v_rcp_f32_e32 v177, v177
	v_rcp_f32_e32 v179, v179
	v_rcp_f32_e32 v139, v139
	v_pk_mul_f32 v[168:169], v[168:169], v[136:137]
	v_pk_mul_f32 v[166:167], v[166:167], v[176:177]
	v_pk_mul_f32 v[140:141], v[140:141], v[178:179]
	v_pk_mul_f32 v[142:143], v[142:143], v[138:139]
.LBB0_207:
	s_lshl_b32 s19, s26, 8
	s_add_i32 s19, s19, s51
	v_add_u32_e32 v175, s19, v175
	v_cndmask_b32_e64 v136, v174, 1.0, s[28:29]
	v_mad_u32_u24 v138, v175, s71, v248
	v_pk_mul_f32 v[166:167], v[136:137], v[166:167] op_sel_hi:[0,1]
	v_pk_mul_f32 v[168:169], v[136:137], v[168:169] op_sel_hi:[0,1]
	v_pk_mul_f32 v[176:177], v[136:137], v[140:141] op_sel_hi:[0,1]
	v_pk_mul_f32 v[142:143], v[136:137], v[142:143] op_sel_hi:[0,1]
	v_cvt_pk_bf16_f32 v140, v168, v169
	v_cvt_pk_bf16_f32 v141, v166, v167
	v_cvt_pk_bf16_f32 v142, v142, v143
	v_cvt_pk_bf16_f32 v143, v176, v177
	global_store_dwordx4 v138, v[140:143], s[8:9] nt
	v_pk_add_f32 v[134:135], v[134:135], v[62:63]
	v_pk_add_f32 v[132:133], v[132:133], v[60:61]
	v_pk_add_f32 v[130:131], v[130:131], v[54:55]
	s_and_b64 vcc, exec, s[4:5]
	v_pk_add_f32 v[140:141], v[128:129], v[52:53]
	s_cbranch_vccnz .LBB0_209
	v_mul_f32_e32 v143, 0xbfb8aa3b, v134
	v_mul_f32_e32 v129, 0xbfb8aa3b, v140
	v_exp_f32_e32 v143, v143
	v_mul_f32_e32 v166, 0xbfb8aa3b, v130
	v_mul_f32_e32 v137, 0xbfb8aa3b, v133
	v_exp_f32_e32 v129, v129
	v_exp_f32_e32 v167, v166
	v_exp_f32_e32 v137, v137
	v_add_f32_e32 v143, 1.0, v143
	v_add_f32_e32 v129, 1.0, v129
	v_rcp_f32_e32 v166, v143
	v_add_f32_e32 v143, 1.0, v167
	v_mul_f32_e32 v167, 0xbfb8aa3b, v135
	v_mul_f32_e32 v128, 0xbfb8aa3b, v132
	v_rcp_f32_e32 v142, v129
	v_add_f32_e32 v129, 1.0, v137
	v_mul_f32_e32 v137, 0xbfb8aa3b, v141
	v_exp_f32_e32 v167, v167
	v_mul_f32_e32 v168, 0xbfb8aa3b, v131
	v_exp_f32_e32 v128, v128
	v_exp_f32_e32 v137, v137
	v_exp_f32_e32 v169, v168
	v_rcp_f32_e32 v168, v143
	v_add_f32_e32 v143, 1.0, v167
	v_add_f32_e32 v128, 1.0, v128
	v_add_f32_e32 v137, 1.0, v137
	v_rcp_f32_e32 v167, v143
	v_add_f32_e32 v143, 1.0, v169
	v_rcp_f32_e32 v128, v128
	v_rcp_f32_e32 v129, v129
	v_rcp_f32_e32 v169, v143
	v_rcp_f32_e32 v143, v137
	v_pk_mul_f32 v[134:135], v[134:135], v[166:167]
	v_pk_mul_f32 v[132:133], v[132:133], v[128:129]
	v_pk_mul_f32 v[130:131], v[130:131], v[168:169]
	v_pk_mul_f32 v[140:141], v[140:141], v[142:143]
.LBB0_209:
	v_mov_b32_e32 v137, v136
	v_mov_b32_e32 v128, v136
	v_mov_b32_e32 v129, v136
	v_pk_mul_f32 v[134:135], v[128:129], v[134:135]
	v_pk_mul_f32 v[132:133], v[136:137], v[132:133]
	v_pk_mul_f32 v[142:143], v[128:129], v[130:131]
	v_cvt_pk_bf16_f32 v130, v132, v133
	v_cvt_pk_bf16_f32 v131, v134, v135
	v_pk_mul_f32 v[140:141], v[136:137], v[140:141]
	v_pk_add_f32 v[126:127], v[126:127], v[74:75]
	v_cvt_pk_bf16_f32 v132, v140, v141
	v_cvt_pk_bf16_f32 v133, v142, v143
	global_store_dwordx4 v138, v[130:133], s[8:9] offset:256 nt
	v_pk_add_f32 v[124:125], v[124:125], v[72:73]
	v_pk_add_f32 v[122:123], v[122:123], v[66:67]
	s_and_b64 vcc, exec, s[4:5]
	v_pk_add_f32 v[130:131], v[120:121], v[64:65]
	s_cbranch_vccnz .LBB0_211
	v_mul_f32_e32 v121, 0xbfb8aa3b, v130
	v_mul_f32_e32 v132, 0xbfb8aa3b, v125
	v_exp_f32_e32 v121, v121
	v_exp_f32_e32 v133, v132
	v_mul_f32_e32 v135, 0xbfb8aa3b, v122
	v_mul_f32_e32 v138, 0xbfb8aa3b, v127
	v_add_f32_e32 v121, 1.0, v121
	v_mul_f32_e32 v120, 0xbfb8aa3b, v124
	v_rcp_f32_e32 v132, v121
	v_add_f32_e32 v121, 1.0, v133
	v_mul_f32_e32 v133, 0xbfb8aa3b, v131
	v_mul_f32_e32 v134, 0xbfb8aa3b, v126
	v_exp_f32_e32 v135, v135
	v_exp_f32_e32 v139, v138
	v_mul_f32_e32 v138, 0xbfb8aa3b, v123
	v_exp_f32_e32 v120, v120
	v_exp_f32_e32 v133, v133
	v_exp_f32_e32 v134, v134
	v_exp_f32_e32 v140, v138
	v_add_f32_e32 v135, 1.0, v135
	v_add_f32_e32 v120, 1.0, v120
	v_add_f32_e32 v133, 1.0, v133
	v_add_f32_e32 v134, 1.0, v134
	v_rcp_f32_e32 v138, v135
	v_add_f32_e32 v135, 1.0, v139
	v_add_f32_e32 v139, 1.0, v140
	v_rcp_f32_e32 v120, v120
	v_rcp_f32_e32 v121, v121
	v_rcp_f32_e32 v134, v134
	v_rcp_f32_e32 v135, v135
	v_rcp_f32_e32 v139, v139
	v_rcp_f32_e32 v133, v133
	v_pk_mul_f32 v[124:125], v[124:125], v[120:121]
	v_pk_mul_f32 v[126:127], v[126:127], v[134:135]
	v_pk_mul_f32 v[122:123], v[122:123], v[138:139]
	v_pk_mul_f32 v[130:131], v[130:131], v[132:133]
.LBB0_211:
	v_add_u32_e32 v132, 16, v175
	v_mad_u32_u24 v120, v132, s71, v248
	v_pk_mul_f32 v[126:127], v[128:129], v[126:127]
	v_pk_mul_f32 v[124:125], v[136:137], v[124:125]
	v_pk_mul_f32 v[128:129], v[128:129], v[122:123]
	v_cvt_pk_bf16_f32 v122, v124, v125
	v_cvt_pk_bf16_f32 v123, v126, v127
	v_pk_mul_f32 v[130:131], v[136:137], v[130:131]
	v_pk_add_f32 v[118:119], v[118:119], v[62:63]
	v_cvt_pk_bf16_f32 v124, v130, v131
	v_cvt_pk_bf16_f32 v125, v128, v129
	global_store_dwordx4 v120, v[122:125], s[8:9] nt
	v_pk_add_f32 v[116:117], v[116:117], v[60:61]
	v_pk_add_f32 v[114:115], v[114:115], v[54:55]
	s_and_b64 vcc, exec, s[4:5]
	v_pk_add_f32 v[122:123], v[112:113], v[52:53]
	s_cbranch_vccnz .LBB0_213
	v_mul_f32_e32 v113, 0xbfb8aa3b, v122
	v_mul_f32_e32 v124, 0xbfb8aa3b, v117
	v_exp_f32_e32 v113, v113
	v_exp_f32_e32 v125, v124
	v_mul_f32_e32 v127, 0xbfb8aa3b, v114
	v_mul_f32_e32 v128, 0xbfb8aa3b, v119
	v_add_f32_e32 v113, 1.0, v113
	v_mul_f32_e32 v112, 0xbfb8aa3b, v116
	v_rcp_f32_e32 v124, v113
	v_add_f32_e32 v113, 1.0, v125
	v_mul_f32_e32 v125, 0xbfb8aa3b, v123
	v_mul_f32_e32 v126, 0xbfb8aa3b, v118
	v_exp_f32_e32 v127, v127
	v_exp_f32_e32 v129, v128
	v_mul_f32_e32 v128, 0xbfb8aa3b, v115
	v_exp_f32_e32 v112, v112
	v_exp_f32_e32 v125, v125
	v_exp_f32_e32 v126, v126
	v_exp_f32_e32 v130, v128
	v_add_f32_e32 v127, 1.0, v127
	v_add_f32_e32 v112, 1.0, v112
	v_add_f32_e32 v125, 1.0, v125
	v_add_f32_e32 v126, 1.0, v126
	v_rcp_f32_e32 v128, v127
	v_add_f32_e32 v127, 1.0, v129
	v_add_f32_e32 v129, 1.0, v130
	v_rcp_f32_e32 v112, v112
	v_rcp_f32_e32 v113, v113
	v_rcp_f32_e32 v126, v126
	v_rcp_f32_e32 v127, v127
	v_rcp_f32_e32 v129, v129
	v_rcp_f32_e32 v125, v125
	v_pk_mul_f32 v[116:117], v[116:117], v[112:113]
	v_pk_mul_f32 v[118:119], v[118:119], v[126:127]
	v_pk_mul_f32 v[114:115], v[114:115], v[128:129]
	v_pk_mul_f32 v[122:123], v[122:123], v[124:125]
.LBB0_213:
	v_mov_b32_e32 v112, v136
	v_mov_b32_e32 v113, v136
	v_pk_mul_f32 v[118:119], v[112:113], v[118:119]
	v_pk_mul_f32 v[116:117], v[136:137], v[116:117]
	v_pk_mul_f32 v[124:125], v[112:113], v[114:115]
	v_cvt_pk_bf16_f32 v114, v116, v117
	v_cvt_pk_bf16_f32 v115, v118, v119
	v_pk_mul_f32 v[122:123], v[136:137], v[122:123]
	v_pk_add_f32 v[110:111], v[110:111], v[74:75]
	v_cvt_pk_bf16_f32 v116, v122, v123
	v_cvt_pk_bf16_f32 v117, v124, v125
	global_store_dwordx4 v120, v[114:117], s[8:9] offset:256 nt
	v_pk_add_f32 v[108:109], v[108:109], v[72:73]
	v_pk_add_f32 v[106:107], v[106:107], v[66:67]
	s_and_b64 vcc, exec, s[4:5]
	v_pk_add_f32 v[114:115], v[104:105], v[64:65]
	s_cbranch_vccnz .LBB0_215
	v_mul_f32_e32 v105, 0xbfb8aa3b, v114
	v_mul_f32_e32 v116, 0xbfb8aa3b, v109
	v_exp_f32_e32 v105, v105
	v_exp_f32_e32 v117, v116
	v_mul_f32_e32 v119, 0xbfb8aa3b, v106
	v_mul_f32_e32 v120, 0xbfb8aa3b, v111
	v_add_f32_e32 v105, 1.0, v105
	v_mul_f32_e32 v104, 0xbfb8aa3b, v108
	v_rcp_f32_e32 v116, v105
	v_add_f32_e32 v105, 1.0, v117
	v_mul_f32_e32 v117, 0xbfb8aa3b, v115
	v_mul_f32_e32 v118, 0xbfb8aa3b, v110
	v_exp_f32_e32 v119, v119
	v_exp_f32_e32 v121, v120
	v_mul_f32_e32 v120, 0xbfb8aa3b, v107
	v_exp_f32_e32 v104, v104
	v_exp_f32_e32 v117, v117
	v_exp_f32_e32 v118, v118
	v_exp_f32_e32 v122, v120
	v_add_f32_e32 v119, 1.0, v119
	v_add_f32_e32 v104, 1.0, v104
	v_add_f32_e32 v117, 1.0, v117
	v_add_f32_e32 v118, 1.0, v118
	v_rcp_f32_e32 v120, v119
	v_add_f32_e32 v119, 1.0, v121
	v_add_f32_e32 v121, 1.0, v122
	v_rcp_f32_e32 v104, v104
	v_rcp_f32_e32 v105, v105
	v_rcp_f32_e32 v118, v118
	v_rcp_f32_e32 v119, v119
	v_rcp_f32_e32 v121, v121
	v_rcp_f32_e32 v117, v117
	v_pk_mul_f32 v[108:109], v[108:109], v[104:105]
	v_pk_mul_f32 v[110:111], v[110:111], v[118:119]
	v_pk_mul_f32 v[106:107], v[106:107], v[120:121]
	v_pk_mul_f32 v[114:115], v[114:115], v[116:117]
.LBB0_215:
	v_add_u32_e32 v116, 32, v175
	v_mad_u32_u24 v104, v116, s71, v248
	v_pk_mul_f32 v[110:111], v[112:113], v[110:111]
	v_pk_mul_f32 v[108:109], v[136:137], v[108:109]
	v_pk_mul_f32 v[112:113], v[112:113], v[106:107]
	v_cvt_pk_bf16_f32 v106, v108, v109
	v_cvt_pk_bf16_f32 v107, v110, v111
	v_pk_mul_f32 v[114:115], v[136:137], v[114:115]
	v_pk_add_f32 v[102:103], v[102:103], v[62:63]
	v_cvt_pk_bf16_f32 v108, v114, v115
	v_cvt_pk_bf16_f32 v109, v112, v113
	global_store_dwordx4 v104, v[106:109], s[8:9] nt
	v_pk_add_f32 v[100:101], v[100:101], v[60:61]
	v_pk_add_f32 v[98:99], v[98:99], v[54:55]
	s_and_b64 vcc, exec, s[4:5]
	v_pk_add_f32 v[106:107], v[96:97], v[52:53]
	s_cbranch_vccnz .LBB0_217
	v_mul_f32_e32 v97, 0xbfb8aa3b, v106
	v_mul_f32_e32 v108, 0xbfb8aa3b, v101
	v_exp_f32_e32 v97, v97
	v_exp_f32_e32 v109, v108
	v_mul_f32_e32 v111, 0xbfb8aa3b, v98
	v_mul_f32_e32 v112, 0xbfb8aa3b, v103
	v_add_f32_e32 v97, 1.0, v97
	v_mul_f32_e32 v96, 0xbfb8aa3b, v100
	v_rcp_f32_e32 v108, v97
	v_add_f32_e32 v97, 1.0, v109
	v_mul_f32_e32 v109, 0xbfb8aa3b, v107
	v_mul_f32_e32 v110, 0xbfb8aa3b, v102
	v_exp_f32_e32 v111, v111
	v_exp_f32_e32 v113, v112
	v_mul_f32_e32 v112, 0xbfb8aa3b, v99
	v_exp_f32_e32 v96, v96
	v_exp_f32_e32 v109, v109
	v_exp_f32_e32 v110, v110
	v_exp_f32_e32 v114, v112
	v_add_f32_e32 v111, 1.0, v111
	v_add_f32_e32 v96, 1.0, v96
	v_add_f32_e32 v109, 1.0, v109
	v_add_f32_e32 v110, 1.0, v110
	v_rcp_f32_e32 v112, v111
	v_add_f32_e32 v111, 1.0, v113
	v_add_f32_e32 v113, 1.0, v114
	v_rcp_f32_e32 v96, v96
	v_rcp_f32_e32 v97, v97
	v_rcp_f32_e32 v110, v110
	v_rcp_f32_e32 v111, v111
	v_rcp_f32_e32 v113, v113
	v_rcp_f32_e32 v109, v109
	v_pk_mul_f32 v[100:101], v[100:101], v[96:97]
	v_pk_mul_f32 v[102:103], v[102:103], v[110:111]
	v_pk_mul_f32 v[98:99], v[98:99], v[112:113]
	v_pk_mul_f32 v[106:107], v[106:107], v[108:109]
.LBB0_217:
	v_mov_b32_e32 v96, v136
	v_mov_b32_e32 v97, v136
	v_pk_mul_f32 v[102:103], v[96:97], v[102:103]
	v_pk_mul_f32 v[100:101], v[136:137], v[100:101]
	v_pk_mul_f32 v[108:109], v[96:97], v[98:99]
	v_cvt_pk_bf16_f32 v98, v100, v101
	v_cvt_pk_bf16_f32 v99, v102, v103
	v_pk_mul_f32 v[106:107], v[136:137], v[106:107]
	v_pk_add_f32 v[94:95], v[94:95], v[74:75]
	v_cvt_pk_bf16_f32 v100, v106, v107
	v_cvt_pk_bf16_f32 v101, v108, v109
	global_store_dwordx4 v104, v[98:101], s[8:9] offset:256 nt
	v_pk_add_f32 v[92:93], v[92:93], v[72:73]
	v_pk_add_f32 v[90:91], v[90:91], v[66:67]
	s_and_b64 vcc, exec, s[4:5]
	v_pk_add_f32 v[98:99], v[88:89], v[64:65]
	s_cbranch_vccnz .LBB0_219
	v_mul_f32_e32 v89, 0xbfb8aa3b, v98
	v_mul_f32_e32 v100, 0xbfb8aa3b, v93
	v_exp_f32_e32 v89, v89
	v_exp_f32_e32 v101, v100
	v_mul_f32_e32 v103, 0xbfb8aa3b, v90
	v_mul_f32_e32 v104, 0xbfb8aa3b, v95
	v_add_f32_e32 v89, 1.0, v89
	v_mul_f32_e32 v88, 0xbfb8aa3b, v92
	v_rcp_f32_e32 v100, v89
	v_add_f32_e32 v89, 1.0, v101
	v_mul_f32_e32 v101, 0xbfb8aa3b, v99
	v_mul_f32_e32 v102, 0xbfb8aa3b, v94
	v_exp_f32_e32 v103, v103
	v_exp_f32_e32 v105, v104
	v_mul_f32_e32 v104, 0xbfb8aa3b, v91
	v_exp_f32_e32 v88, v88
	v_exp_f32_e32 v101, v101
	v_exp_f32_e32 v102, v102
	v_exp_f32_e32 v106, v104
	v_add_f32_e32 v103, 1.0, v103
	v_add_f32_e32 v88, 1.0, v88
	v_add_f32_e32 v101, 1.0, v101
	v_add_f32_e32 v102, 1.0, v102
	v_rcp_f32_e32 v104, v103
	v_add_f32_e32 v103, 1.0, v105
	v_add_f32_e32 v105, 1.0, v106
	v_rcp_f32_e32 v88, v88
	v_rcp_f32_e32 v89, v89
	v_rcp_f32_e32 v102, v102
	v_rcp_f32_e32 v103, v103
	v_rcp_f32_e32 v105, v105
	v_rcp_f32_e32 v101, v101
	v_pk_mul_f32 v[92:93], v[92:93], v[88:89]
	v_pk_mul_f32 v[94:95], v[94:95], v[102:103]
	v_pk_mul_f32 v[90:91], v[90:91], v[104:105]
	v_pk_mul_f32 v[98:99], v[98:99], v[100:101]
.LBB0_219:
	v_add_u32_e32 v100, 48, v175
	v_mad_u32_u24 v88, v100, s71, v248
	v_pk_mul_f32 v[94:95], v[96:97], v[94:95]
	v_pk_mul_f32 v[92:93], v[136:137], v[92:93]
	v_pk_mul_f32 v[96:97], v[96:97], v[90:91]
	v_cvt_pk_bf16_f32 v90, v92, v93
	v_cvt_pk_bf16_f32 v91, v94, v95
	v_pk_mul_f32 v[98:99], v[136:137], v[98:99]
	v_pk_add_f32 v[86:87], v[86:87], v[62:63]
	v_cvt_pk_bf16_f32 v92, v98, v99
	v_cvt_pk_bf16_f32 v93, v96, v97
	global_store_dwordx4 v88, v[90:93], s[8:9] nt
	v_pk_add_f32 v[84:85], v[84:85], v[60:61]
	v_pk_add_f32 v[82:83], v[82:83], v[54:55]
	s_and_b64 vcc, exec, s[4:5]
	v_pk_add_f32 v[90:91], v[80:81], v[52:53]
	s_cbranch_vccnz .LBB0_221
	v_mul_f32_e32 v81, 0xbfb8aa3b, v90
	v_mul_f32_e32 v92, 0xbfb8aa3b, v85
	v_exp_f32_e32 v81, v81
	v_exp_f32_e32 v93, v92
	v_mul_f32_e32 v95, 0xbfb8aa3b, v82
	v_mul_f32_e32 v96, 0xbfb8aa3b, v87
	v_add_f32_e32 v81, 1.0, v81
	v_mul_f32_e32 v80, 0xbfb8aa3b, v84
	v_rcp_f32_e32 v92, v81
	v_add_f32_e32 v81, 1.0, v93
	v_mul_f32_e32 v93, 0xbfb8aa3b, v91
	v_mul_f32_e32 v94, 0xbfb8aa3b, v86
	v_exp_f32_e32 v95, v95
	v_exp_f32_e32 v97, v96
	v_mul_f32_e32 v96, 0xbfb8aa3b, v83
	v_exp_f32_e32 v80, v80
	v_exp_f32_e32 v93, v93
	v_exp_f32_e32 v94, v94
	v_exp_f32_e32 v98, v96
	v_add_f32_e32 v95, 1.0, v95
	v_add_f32_e32 v80, 1.0, v80
	v_add_f32_e32 v93, 1.0, v93
	v_add_f32_e32 v94, 1.0, v94
	v_rcp_f32_e32 v96, v95
	v_add_f32_e32 v95, 1.0, v97
	v_add_f32_e32 v97, 1.0, v98
	v_rcp_f32_e32 v80, v80
	v_rcp_f32_e32 v81, v81
	v_rcp_f32_e32 v94, v94
	v_rcp_f32_e32 v95, v95
	v_rcp_f32_e32 v97, v97
	v_rcp_f32_e32 v93, v93
	v_pk_mul_f32 v[84:85], v[84:85], v[80:81]
	v_pk_mul_f32 v[86:87], v[86:87], v[94:95]
	v_pk_mul_f32 v[82:83], v[82:83], v[96:97]
	v_pk_mul_f32 v[90:91], v[90:91], v[92:93]
.LBB0_221:
	v_mov_b32_e32 v80, v136
	v_mov_b32_e32 v81, v136
	v_pk_mul_f32 v[86:87], v[80:81], v[86:87]
	v_pk_mul_f32 v[84:85], v[136:137], v[84:85]
	v_pk_mul_f32 v[92:93], v[80:81], v[82:83]
	v_cvt_pk_bf16_f32 v82, v84, v85
	v_cvt_pk_bf16_f32 v83, v86, v87
	v_pk_mul_f32 v[90:91], v[136:137], v[90:91]
	v_pk_add_f32 v[78:79], v[78:79], v[74:75]
	v_cvt_pk_bf16_f32 v84, v90, v91
	v_cvt_pk_bf16_f32 v85, v92, v93
	global_store_dwordx4 v88, v[82:85], s[8:9] offset:256 nt
	v_pk_add_f32 v[76:77], v[76:77], v[72:73]
	v_pk_add_f32 v[70:71], v[70:71], v[66:67]
	s_and_b64 vcc, exec, s[4:5]
	v_pk_add_f32 v[82:83], v[68:69], v[64:65]
	s_cbranch_vccnz .LBB0_223
	v_mul_f32_e32 v69, 0xbfb8aa3b, v82
	v_mul_f32_e32 v84, 0xbfb8aa3b, v77
	v_exp_f32_e32 v69, v69
	v_exp_f32_e32 v85, v84
	v_mul_f32_e32 v87, 0xbfb8aa3b, v70
	v_mul_f32_e32 v88, 0xbfb8aa3b, v79
	v_add_f32_e32 v69, 1.0, v69
	v_mul_f32_e32 v68, 0xbfb8aa3b, v76
	v_rcp_f32_e32 v84, v69
	v_add_f32_e32 v69, 1.0, v85
	v_mul_f32_e32 v85, 0xbfb8aa3b, v83
	v_mul_f32_e32 v86, 0xbfb8aa3b, v78
	v_exp_f32_e32 v87, v87
	v_exp_f32_e32 v89, v88
	v_mul_f32_e32 v88, 0xbfb8aa3b, v71
	v_exp_f32_e32 v68, v68
	v_exp_f32_e32 v85, v85
	v_exp_f32_e32 v86, v86
	v_exp_f32_e32 v90, v88
	v_add_f32_e32 v87, 1.0, v87
	v_add_f32_e32 v68, 1.0, v68
	v_add_f32_e32 v85, 1.0, v85
	v_add_f32_e32 v86, 1.0, v86
	v_rcp_f32_e32 v88, v87
	v_add_f32_e32 v87, 1.0, v89
	v_add_f32_e32 v89, 1.0, v90
	v_rcp_f32_e32 v68, v68
	v_rcp_f32_e32 v69, v69
	v_rcp_f32_e32 v86, v86
	v_rcp_f32_e32 v87, v87
	v_rcp_f32_e32 v89, v89
	v_rcp_f32_e32 v85, v85
	v_pk_mul_f32 v[76:77], v[76:77], v[68:69]
	v_pk_mul_f32 v[78:79], v[78:79], v[86:87]
	v_pk_mul_f32 v[70:71], v[70:71], v[88:89]
	v_pk_mul_f32 v[82:83], v[82:83], v[84:85]
.LBB0_223:
	v_add_u32_e32 v84, 0x80, v175
	v_pk_mul_f32 v[78:79], v[80:81], v[78:79]
	v_pk_mul_f32 v[76:77], v[136:137], v[76:77]
	v_pk_mul_f32 v[70:71], v[80:81], v[70:71]
	v_mad_u32_u24 v68, v84, s71, v248
	v_pk_mul_f32 v[80:81], v[136:137], v[82:83]
	v_cvt_pk_bf16_f32 v76, v76, v77
	v_cvt_pk_bf16_f32 v77, v78, v79
	v_pk_add_f32 v[58:59], v[58:59], v[62:63]
	v_cvt_pk_bf16_f32 v78, v80, v81
	v_cvt_pk_bf16_f32 v79, v70, v71
	v_pk_add_f32 v[56:57], v[56:57], v[60:61]
	v_pk_add_f32 v[50:51], v[50:51], v[54:55]
	s_and_b64 vcc, exec, s[4:5]
	v_pk_add_f32 v[70:71], v[48:49], v[52:53]
	global_store_dwordx4 v68, v[76:79], s[8:9] nt
	s_cbranch_vccnz .LBB0_225
	v_mul_f32_e32 v49, 0xbfb8aa3b, v70
	v_mul_f32_e32 v76, 0xbfb8aa3b, v57
	v_exp_f32_e32 v49, v49
	v_exp_f32_e32 v77, v76
	v_mul_f32_e32 v79, 0xbfb8aa3b, v50
	v_mul_f32_e32 v80, 0xbfb8aa3b, v59
	v_add_f32_e32 v49, 1.0, v49
	v_mul_f32_e32 v48, 0xbfb8aa3b, v56
	v_rcp_f32_e32 v76, v49
	v_add_f32_e32 v49, 1.0, v77
	v_mul_f32_e32 v77, 0xbfb8aa3b, v71
	v_mul_f32_e32 v78, 0xbfb8aa3b, v58
	v_exp_f32_e32 v79, v79
	v_exp_f32_e32 v81, v80
	v_mul_f32_e32 v80, 0xbfb8aa3b, v51
	v_exp_f32_e32 v48, v48
	v_exp_f32_e32 v77, v77
	v_exp_f32_e32 v78, v78
	v_exp_f32_e32 v82, v80
	v_add_f32_e32 v79, 1.0, v79
	v_add_f32_e32 v48, 1.0, v48
	v_add_f32_e32 v77, 1.0, v77
	v_add_f32_e32 v78, 1.0, v78
	v_rcp_f32_e32 v80, v79
	v_add_f32_e32 v79, 1.0, v81
	v_add_f32_e32 v81, 1.0, v82
	v_rcp_f32_e32 v48, v48
	v_rcp_f32_e32 v49, v49
	v_rcp_f32_e32 v78, v78
	v_rcp_f32_e32 v79, v79
	v_rcp_f32_e32 v81, v81
	v_rcp_f32_e32 v77, v77
	v_pk_mul_f32 v[56:57], v[56:57], v[48:49]
	v_pk_mul_f32 v[58:59], v[58:59], v[78:79]
	v_pk_mul_f32 v[50:51], v[50:51], v[80:81]
	v_pk_mul_f32 v[70:71], v[70:71], v[76:77]
.LBB0_225:
	v_mov_b32_e32 v48, v136
	v_mov_b32_e32 v49, v136
	v_pk_mul_f32 v[58:59], v[48:49], v[58:59]
	v_pk_mul_f32 v[56:57], v[136:137], v[56:57]
	v_pk_mul_f32 v[50:51], v[48:49], v[50:51]
	v_pk_mul_f32 v[70:71], v[136:137], v[70:71]
	v_cvt_pk_bf16_f32 v56, v56, v57
	v_cvt_pk_bf16_f32 v57, v58, v59
	v_pk_add_f32 v[46:47], v[46:47], v[74:75]
	v_cvt_pk_bf16_f32 v58, v70, v71
	v_cvt_pk_bf16_f32 v59, v50, v51
	v_pk_add_f32 v[44:45], v[44:45], v[72:73]
	v_pk_add_f32 v[42:43], v[42:43], v[66:67]
	s_and_b64 vcc, exec, s[4:5]
	v_pk_add_f32 v[50:51], v[40:41], v[64:65]
	global_store_dwordx4 v68, v[56:59], s[8:9] offset:256 nt
	s_cbranch_vccnz .LBB0_227
	v_mul_f32_e32 v41, 0xbfb8aa3b, v50
	v_mul_f32_e32 v56, 0xbfb8aa3b, v45
	v_exp_f32_e32 v41, v41
	v_exp_f32_e32 v57, v56
	v_mul_f32_e32 v59, 0xbfb8aa3b, v42
	v_mul_f32_e32 v68, 0xbfb8aa3b, v47
	v_add_f32_e32 v41, 1.0, v41
	v_mul_f32_e32 v40, 0xbfb8aa3b, v44
	v_rcp_f32_e32 v56, v41
	v_add_f32_e32 v41, 1.0, v57
	v_mul_f32_e32 v57, 0xbfb8aa3b, v51
	v_mul_f32_e32 v58, 0xbfb8aa3b, v46
	v_exp_f32_e32 v59, v59
	v_exp_f32_e32 v69, v68
	v_mul_f32_e32 v68, 0xbfb8aa3b, v43
	v_exp_f32_e32 v40, v40
	v_exp_f32_e32 v57, v57
	v_exp_f32_e32 v58, v58
	v_exp_f32_e32 v70, v68
	v_add_f32_e32 v59, 1.0, v59
	v_add_f32_e32 v40, 1.0, v40
	v_add_f32_e32 v57, 1.0, v57
	v_add_f32_e32 v58, 1.0, v58
	v_rcp_f32_e32 v68, v59
	v_add_f32_e32 v59, 1.0, v69
	v_add_f32_e32 v69, 1.0, v70
	v_rcp_f32_e32 v40, v40
	v_rcp_f32_e32 v41, v41
	v_rcp_f32_e32 v58, v58
	v_rcp_f32_e32 v59, v59
	v_rcp_f32_e32 v69, v69
	v_rcp_f32_e32 v57, v57
	v_pk_mul_f32 v[44:45], v[44:45], v[40:41]
	v_pk_mul_f32 v[46:47], v[46:47], v[58:59]
	v_pk_mul_f32 v[42:43], v[42:43], v[68:69]
	v_pk_mul_f32 v[50:51], v[50:51], v[56:57]
.LBB0_227:
	s_nop 0
	v_add_u32_e32 v56, 0x90, v175
	v_mad_u32_u24 v40, v56, s71, v248
	v_pk_mul_f32 v[46:47], v[48:49], v[46:47]
	v_pk_mul_f32 v[44:45], v[136:137], v[44:45]
	v_pk_mul_f32 v[48:49], v[48:49], v[42:43]
	v_cvt_pk_bf16_f32 v42, v44, v45
	v_cvt_pk_bf16_f32 v43, v46, v47
	v_pk_mul_f32 v[50:51], v[136:137], v[50:51]
	v_pk_add_f32 v[38:39], v[38:39], v[62:63]
	v_cvt_pk_bf16_f32 v44, v50, v51
	v_cvt_pk_bf16_f32 v45, v48, v49
	global_store_dwordx4 v40, v[42:45], s[8:9] nt
	v_pk_add_f32 v[36:37], v[36:37], v[60:61]
	v_pk_add_f32 v[34:35], v[34:35], v[54:55]
	s_and_b64 vcc, exec, s[4:5]
	v_pk_add_f32 v[42:43], v[32:33], v[52:53]
	s_cbranch_vccnz .LBB0_229
	v_mul_f32_e32 v33, 0xbfb8aa3b, v42
	v_mul_f32_e32 v44, 0xbfb8aa3b, v37
	v_exp_f32_e32 v33, v33
	v_exp_f32_e32 v45, v44
	v_mul_f32_e32 v47, 0xbfb8aa3b, v34
	v_mul_f32_e32 v48, 0xbfb8aa3b, v39
	v_add_f32_e32 v33, 1.0, v33
	v_mul_f32_e32 v32, 0xbfb8aa3b, v36
	v_rcp_f32_e32 v44, v33
	v_add_f32_e32 v33, 1.0, v45
	v_mul_f32_e32 v45, 0xbfb8aa3b, v43
	v_mul_f32_e32 v46, 0xbfb8aa3b, v38
	v_exp_f32_e32 v47, v47
	v_exp_f32_e32 v49, v48
	v_mul_f32_e32 v48, 0xbfb8aa3b, v35
	v_exp_f32_e32 v32, v32
	v_exp_f32_e32 v45, v45
	v_exp_f32_e32 v46, v46
	v_exp_f32_e32 v50, v48
	v_add_f32_e32 v47, 1.0, v47
	v_add_f32_e32 v32, 1.0, v32
	v_add_f32_e32 v45, 1.0, v45
	v_add_f32_e32 v46, 1.0, v46
	v_rcp_f32_e32 v48, v47
	v_add_f32_e32 v47, 1.0, v49
	v_add_f32_e32 v49, 1.0, v50
	v_rcp_f32_e32 v32, v32
	v_rcp_f32_e32 v33, v33
	v_rcp_f32_e32 v46, v46
	v_rcp_f32_e32 v47, v47
	v_rcp_f32_e32 v49, v49
	v_rcp_f32_e32 v45, v45
	v_pk_mul_f32 v[36:37], v[36:37], v[32:33]
	v_pk_mul_f32 v[38:39], v[38:39], v[46:47]
	v_pk_mul_f32 v[34:35], v[34:35], v[48:49]
	v_pk_mul_f32 v[42:43], v[42:43], v[44:45]
.LBB0_229:
	v_mov_b32_e32 v32, v136
	v_mov_b32_e32 v33, v136
	v_pk_mul_f32 v[38:39], v[32:33], v[38:39]
	v_pk_mul_f32 v[36:37], v[136:137], v[36:37]
	v_pk_mul_f32 v[44:45], v[32:33], v[34:35]
	v_cvt_pk_bf16_f32 v34, v36, v37
	v_cvt_pk_bf16_f32 v35, v38, v39
	v_pk_mul_f32 v[42:43], v[136:137], v[42:43]
	v_pk_add_f32 v[30:31], v[30:31], v[74:75]
	v_cvt_pk_bf16_f32 v36, v42, v43
	v_cvt_pk_bf16_f32 v37, v44, v45
	global_store_dwordx4 v40, v[34:37], s[8:9] offset:256 nt
	v_pk_add_f32 v[28:29], v[28:29], v[72:73]
	v_pk_add_f32 v[26:27], v[26:27], v[66:67]
	s_and_b64 vcc, exec, s[4:5]
	v_pk_add_f32 v[34:35], v[24:25], v[64:65]
	s_cbranch_vccnz .LBB0_231
	v_mul_f32_e32 v25, 0xbfb8aa3b, v34
	v_mul_f32_e32 v36, 0xbfb8aa3b, v29
	v_exp_f32_e32 v25, v25
	v_exp_f32_e32 v37, v36
	v_mul_f32_e32 v39, 0xbfb8aa3b, v26
	v_mul_f32_e32 v40, 0xbfb8aa3b, v31
	v_add_f32_e32 v25, 1.0, v25
	v_mul_f32_e32 v24, 0xbfb8aa3b, v28
	v_rcp_f32_e32 v36, v25
	v_add_f32_e32 v25, 1.0, v37
	v_mul_f32_e32 v37, 0xbfb8aa3b, v35
	v_mul_f32_e32 v38, 0xbfb8aa3b, v30
	v_exp_f32_e32 v39, v39
	v_exp_f32_e32 v41, v40
	v_mul_f32_e32 v40, 0xbfb8aa3b, v27
	v_exp_f32_e32 v24, v24
	v_exp_f32_e32 v37, v37
	v_exp_f32_e32 v38, v38
	v_exp_f32_e32 v42, v40
	v_add_f32_e32 v39, 1.0, v39
	v_add_f32_e32 v24, 1.0, v24
	v_add_f32_e32 v37, 1.0, v37
	v_add_f32_e32 v38, 1.0, v38
	v_rcp_f32_e32 v40, v39
	v_add_f32_e32 v39, 1.0, v41
	v_add_f32_e32 v41, 1.0, v42
	v_rcp_f32_e32 v24, v24
	v_rcp_f32_e32 v25, v25
	v_rcp_f32_e32 v38, v38
	v_rcp_f32_e32 v39, v39
	v_rcp_f32_e32 v41, v41
	v_rcp_f32_e32 v37, v37
	v_pk_mul_f32 v[28:29], v[28:29], v[24:25]
	v_pk_mul_f32 v[30:31], v[30:31], v[38:39]
	v_pk_mul_f32 v[26:27], v[26:27], v[40:41]
	v_pk_mul_f32 v[34:35], v[34:35], v[36:37]
.LBB0_231:
	v_add_u32_e32 v36, 0xa0, v175
	v_mad_u32_u24 v24, v36, s71, v248
	v_pk_mul_f32 v[30:31], v[32:33], v[30:31]
	v_pk_mul_f32 v[28:29], v[136:137], v[28:29]
	v_pk_mul_f32 v[32:33], v[32:33], v[26:27]
	v_cvt_pk_bf16_f32 v26, v28, v29
	v_cvt_pk_bf16_f32 v27, v30, v31
	v_pk_mul_f32 v[34:35], v[136:137], v[34:35]
	v_pk_add_f32 v[22:23], v[22:23], v[62:63]
	v_cvt_pk_bf16_f32 v28, v34, v35
	v_cvt_pk_bf16_f32 v29, v32, v33
	global_store_dwordx4 v24, v[26:29], s[8:9] nt
	v_pk_add_f32 v[20:21], v[20:21], v[60:61]
	v_pk_add_f32 v[18:19], v[18:19], v[54:55]
	s_and_b64 vcc, exec, s[4:5]
	v_pk_add_f32 v[26:27], v[16:17], v[52:53]
	s_cbranch_vccnz .LBB0_233
	v_mul_f32_e32 v17, 0xbfb8aa3b, v26
	v_mul_f32_e32 v28, 0xbfb8aa3b, v21
	v_exp_f32_e32 v17, v17
	v_exp_f32_e32 v29, v28
	v_mul_f32_e32 v31, 0xbfb8aa3b, v18
	v_mul_f32_e32 v32, 0xbfb8aa3b, v23
	v_add_f32_e32 v17, 1.0, v17
	v_mul_f32_e32 v16, 0xbfb8aa3b, v20
	v_rcp_f32_e32 v28, v17
	v_add_f32_e32 v17, 1.0, v29
	v_mul_f32_e32 v29, 0xbfb8aa3b, v27
	v_mul_f32_e32 v30, 0xbfb8aa3b, v22
	v_exp_f32_e32 v31, v31
	v_exp_f32_e32 v33, v32
	v_mul_f32_e32 v32, 0xbfb8aa3b, v19
	v_exp_f32_e32 v16, v16
	v_exp_f32_e32 v29, v29
	v_exp_f32_e32 v30, v30
	v_exp_f32_e32 v34, v32
	v_add_f32_e32 v31, 1.0, v31
	v_add_f32_e32 v16, 1.0, v16
	v_add_f32_e32 v29, 1.0, v29
	v_add_f32_e32 v30, 1.0, v30
	v_rcp_f32_e32 v32, v31
	v_add_f32_e32 v31, 1.0, v33
	v_add_f32_e32 v33, 1.0, v34
	v_rcp_f32_e32 v16, v16
	v_rcp_f32_e32 v17, v17
	v_rcp_f32_e32 v30, v30
	v_rcp_f32_e32 v31, v31
	v_rcp_f32_e32 v33, v33
	v_rcp_f32_e32 v29, v29
	v_pk_mul_f32 v[20:21], v[20:21], v[16:17]
	v_pk_mul_f32 v[22:23], v[22:23], v[30:31]
	v_pk_mul_f32 v[18:19], v[18:19], v[32:33]
	v_pk_mul_f32 v[26:27], v[26:27], v[28:29]
.LBB0_233:
	v_mov_b32_e32 v16, v136
	v_mov_b32_e32 v17, v136
	v_pk_mul_f32 v[22:23], v[16:17], v[22:23]
	v_pk_mul_f32 v[20:21], v[136:137], v[20:21]
	v_pk_mul_f32 v[28:29], v[16:17], v[18:19]
	v_cvt_pk_bf16_f32 v18, v20, v21
	v_cvt_pk_bf16_f32 v19, v22, v23
	v_pk_mul_f32 v[26:27], v[136:137], v[26:27]
	v_pk_add_f32 v[14:15], v[14:15], v[74:75]
	v_cvt_pk_bf16_f32 v20, v26, v27
	v_cvt_pk_bf16_f32 v21, v28, v29
	global_store_dwordx4 v24, v[18:21], s[8:9] offset:256 nt
	v_pk_add_f32 v[12:13], v[12:13], v[72:73]
	v_pk_add_f32 v[10:11], v[10:11], v[66:67]
	s_and_b64 vcc, exec, s[4:5]
	v_pk_add_f32 v[18:19], v[8:9], v[64:65]
	s_cbranch_vccnz .LBB0_235
	v_mul_f32_e32 v9, 0xbfb8aa3b, v18
	v_mul_f32_e32 v20, 0xbfb8aa3b, v13
	v_exp_f32_e32 v9, v9
	v_exp_f32_e32 v21, v20
	v_mul_f32_e32 v23, 0xbfb8aa3b, v10
	v_mul_f32_e32 v24, 0xbfb8aa3b, v15
	v_add_f32_e32 v9, 1.0, v9
	v_mul_f32_e32 v8, 0xbfb8aa3b, v12
	v_rcp_f32_e32 v20, v9
	v_add_f32_e32 v9, 1.0, v21
	v_mul_f32_e32 v21, 0xbfb8aa3b, v19
	v_mul_f32_e32 v22, 0xbfb8aa3b, v14
	v_exp_f32_e32 v23, v23
	v_exp_f32_e32 v25, v24
	v_mul_f32_e32 v24, 0xbfb8aa3b, v11
	v_exp_f32_e32 v8, v8
	v_exp_f32_e32 v21, v21
	v_exp_f32_e32 v22, v22
	v_exp_f32_e32 v26, v24
	v_add_f32_e32 v23, 1.0, v23
	v_add_f32_e32 v8, 1.0, v8
	v_add_f32_e32 v21, 1.0, v21
	v_add_f32_e32 v22, 1.0, v22
	v_rcp_f32_e32 v24, v23
	v_add_f32_e32 v23, 1.0, v25
	v_add_f32_e32 v25, 1.0, v26
	v_rcp_f32_e32 v8, v8
	v_rcp_f32_e32 v9, v9
	v_rcp_f32_e32 v22, v22
	v_rcp_f32_e32 v23, v23
	v_rcp_f32_e32 v25, v25
	v_rcp_f32_e32 v21, v21
	v_pk_mul_f32 v[12:13], v[12:13], v[8:9]
	v_pk_mul_f32 v[14:15], v[14:15], v[22:23]
	v_pk_mul_f32 v[10:11], v[10:11], v[24:25]
	v_pk_mul_f32 v[18:19], v[18:19], v[20:21]
.LBB0_235:
	v_add_u32_e32 v20, 0xb0, v175
	v_mad_u32_u24 v8, v20, s71, v248
	v_pk_mul_f32 v[12:13], v[136:137], v[12:13]
	v_pk_add_f32 v[6:7], v[6:7], v[62:63]
	v_pk_add_f32 v[4:5], v[4:5], v[60:61]
	v_pk_add_f32 v[2:3], v[2:3], v[54:55]
	s_and_b64 vcc, exec, s[4:5]
	v_pk_add_f32 v[0:1], v[0:1], v[52:53]
	v_pk_mul_f32 v[14:15], v[16:17], v[14:15]
	v_pk_mul_f32 v[16:17], v[16:17], v[10:11]
	v_pk_mul_f32 v[18:19], v[136:137], v[18:19]
	v_cvt_pk_bf16_f32 v10, v12, v13
	v_cvt_pk_bf16_f32 v11, v14, v15
	s_nop 0
	v_cvt_pk_bf16_f32 v12, v18, v19
	v_cvt_pk_bf16_f32 v13, v16, v17
	global_store_dwordx4 v8, v[10:13], s[8:9] nt
	s_cbranch_vccnz .LBB0_237
	s_nop 0
	v_mul_f32_e32 v11, 0xbfb8aa3b, v0
	v_mul_f32_e32 v12, 0xbfb8aa3b, v5
	v_exp_f32_e32 v11, v11
	v_exp_f32_e32 v13, v12
	v_mul_f32_e32 v15, 0xbfb8aa3b, v2
	v_mul_f32_e32 v16, 0xbfb8aa3b, v7
	v_add_f32_e32 v11, 1.0, v11
	v_mul_f32_e32 v10, 0xbfb8aa3b, v4
	v_rcp_f32_e32 v12, v11
	v_add_f32_e32 v11, 1.0, v13
	v_mul_f32_e32 v13, 0xbfb8aa3b, v1
	v_mul_f32_e32 v14, 0xbfb8aa3b, v6
	v_exp_f32_e32 v15, v15
	v_exp_f32_e32 v17, v16
	v_mul_f32_e32 v16, 0xbfb8aa3b, v3
	v_exp_f32_e32 v10, v10
	v_exp_f32_e32 v13, v13
	v_exp_f32_e32 v14, v14
	v_exp_f32_e32 v18, v16
	v_add_f32_e32 v15, 1.0, v15
	v_add_f32_e32 v10, 1.0, v10
	v_add_f32_e32 v13, 1.0, v13
	v_add_f32_e32 v14, 1.0, v14
	v_rcp_f32_e32 v16, v15
	v_add_f32_e32 v15, 1.0, v17
	v_add_f32_e32 v17, 1.0, v18
	v_rcp_f32_e32 v10, v10
	v_rcp_f32_e32 v11, v11
	v_rcp_f32_e32 v14, v14
	v_rcp_f32_e32 v15, v15
	v_rcp_f32_e32 v17, v17
	v_rcp_f32_e32 v13, v13
	v_pk_mul_f32 v[4:5], v[4:5], v[10:11]
	v_pk_mul_f32 v[6:7], v[6:7], v[14:15]
	v_pk_mul_f32 v[2:3], v[2:3], v[16:17]
	v_pk_mul_f32 v[0:1], v[0:1], v[12:13]
.LBB0_237:
	s_nop 0
	v_mov_b32_e32 v10, v136
	v_mov_b32_e32 v11, v136
	v_pk_mul_f32 v[6:7], v[10:11], v[6:7]
	v_pk_mul_f32 v[10:11], v[10:11], v[2:3]
	v_pk_mul_f32 v[2:3], v[136:137], v[0:1]
	s_andn2_b64 vcc, exec, s[0:1]
	s_mov_b64 s[0:1], -1
	v_pk_mul_f32 v[4:5], v[136:137], v[4:5]
	s_nop 0
	v_cvt_pk_bf16_f32 v0, v4, v5
	v_cvt_pk_bf16_f32 v1, v6, v7
	v_cvt_pk_bf16_f32 v2, v2, v3
	v_cvt_pk_bf16_f32 v3, v10, v11
	global_store_dwordx4 v8, v[0:3], s[8:9] offset:256 nt
	s_cbranch_vccnz .LBB0_198
	s_andn2_b64 vcc, exec, s[6:7]
	s_cbranch_vccnz .LBB0_197
	s_barrier
	s_branch .LBB0_197
